# phase-0 load balance (WGs 0-31 carry two adaLN partial items, so they take 3 weight-convert rounds instead of 9) + postproc next-item L2 prefetch
# speedup vs baseline: 1.0024x; 1.0006x over previous
; #define LAS __attribute__((address_space(3)))
; __device__ __forceinline__ void convert_ffn(const float* w1, const float* w3, const float* w2, bf16_t* W13, bf16_t* W2, LAS float* scr, int gw, int NGW, int lane) {
;     constexpr int I_UP = 32 * 176, I_DN = 88 * 64;
;     for (int it = gw; it < 2 * I_UP + I_DN; it += NGW) {
;         int r = it;
;         if (r < 2 * I_UP) { const int which = r >= I_UP; if (which) r -= I_UP; const int kb = r / 176, nb = r % 176, n0 = nb * 32;
;             tr_item(which ? w3 : w1, FF_, kb * 64, n0, W13 + (size_t)((n0 >> 7) * 256 + which * 128 + (n0 & 127)) * 2048 + kb * 64, 2048, scr, lane); }
;         else { r -= 2 * I_UP; const int kb = r / 64, nb = r % 64; tr_item(w2, D_, kb * 64, nb * 32, W2 + (size_t)(nb * 32) * FF_ + kb * 64, FF_, scr, lane); }
;     }
; }
.LBB0_12:
	s_add_u32 s34, s26, 0x2c00000
	s_addc_u32 s35, s27, 0
	s_lshl_b32 s4, s2, 3
	v_add_u32_e32 v26, s4, v88
	v_writelane_b32 v253, s4, 0
	s_movk_i32 s4, 0x2100
	v_mul_lo_u32 v2, v88, s4
	s_movk_i32 s4, 0x4200
	s_lshl_b32 s80, s28, 3
	v_add_u32_e32 v19, 16, v2
	v_cmp_gt_i32_e32 vcc, s4, v26
	v_lshrrev_b32_e32 v27, 5, v87
	v_lshrrev_b32_e32 v20, 3, v87
	v_lshlrev_b32_e32 v21, 3, v87
	v_lshlrev_b32_e32 v18, 5, v88
	s_and_saveexec_b64 s[4:5], vcc
	s_cbranch_execz .LBB0_19
	v_and_b32_e32 v8, 31, v1
	v_mov_b32_e32 v3, 0
	v_lshlrev_b32_e32 v2, 2, v8
	v_and_b32_e32 v16, 56, v21
	s_waitcnt lgkmcnt(0)
	v_lshl_add_u64 v[4:5], s[50:51], 0, v[2:3]
	v_add_u32_e32 v6, v19, v2
	v_mul_u32_u24_e32 v7, 0x84, v27
	v_mul_u32_u24_e32 v2, 0x84, v16
	v_lshlrev_b32_e32 v9, 2, v20
	v_lshlrev_b32_e32 v10, 11, v20
	v_add3_u32 v22, v19, v2, v9
	v_mul_u32_u24_e32 v2, 0x1600, v20
	v_or_b32_e32 v12, 0x4000, v10
	v_or_b32_e32 v14, 0x8000, v10
	v_or_b32_e32 v28, 0xc000, v10
	v_add_u32_e32 v24, v6, v7
	v_lshl_add_u32 v23, s2, 8, v18
	s_lshl_b32 s22, s28, 8
	s_mov_b64 s[8:9], 0
	s_movk_i32 s6, 0x2bff
	v_lshlrev_b32_e32 v6, 1, v2
	s_mov_b32 s7, 0x16000
	s_mov_b32 s12, 0x2c000
	s_movk_i32 s13, 0x15ff
	s_mov_b32 s14, 0x2e8ba2e9
	s_movk_i32 s15, 0xb0
	v_lshlrev_b32_e32 v2, 2, v8
	s_movk_i32 s16, 0x5800
	v_lshlrev_b32_e32 v8, 1, v10
	v_lshlrev_b32_e32 v10, 1, v12
	v_lshlrev_b32_e32 v12, 1, v14
	v_lshlrev_b32_e32 v14, 1, v28
	s_movk_i32 s17, 0x41ff
	v_add_u32_e32 v25, 0x400, v24
	v_add_u32_e32 v28, 0x800, v24
	v_add_u32_e32 v29, 0xc00, v24
	v_add_u32_e32 v30, 0x1000, v24
	v_add_u32_e32 v31, 0x1400, v24
	v_add_u32_e32 v32, 0x1800, v24
	v_add_u32_e32 v33, 0x1c00, v24
	v_lshlrev_b32_e32 v16, 1, v16
	v_mov_b32_e32 v34, 0x80
	s_cmp_lt_u32 s2, 32
	s_cbranch_scc1 .Lmy_cvbal_a
	v_add_u32_e32 v35, 0xffffff00, v26
	s_movk_i32 s80, 0x700
	s_movk_i32 s17, 0x3eff
	s_branch .Lmy_cvbal_j
.Lmy_cvbal_a:
	v_add_u32_e32 v35, 0x3f00, v26
	s_movk_i32 s80, 0x100
	s_movk_i32 s17, 0x41ff
.Lmy_cvbal_j:
	v_lshlrev_b32_e32 v23, 5, v35
	s_lshl_b32 s22, s80, 5
	s_branch .LBB0_15

; #define LAS __attribute__((address_space(3)))
; __device__ __forceinline__ void convert_mixer(const Params& p, LAS float* scr, int gw, int NGW, int lane) {
;     bf16_t* WIN1 = (bf16_t*)(p.ws + WS_WIN1); bf16_t* WIN2 = (bf16_t*)(p.ws + WS_WIN2); bf16_t* WPAB = (bf16_t*)(p.ws + WS_WPAB); bf16_t* WOUT = (bf16_t*)(p.ws + WS_WOUT);
;     constexpr int I_IN = 32 * 577, I_P = 32 * 64;
;     for (int it = gw; it < I_IN + 3 * I_P; it += NGW) {
;         int r = it;
;         if (r < I_IN) { const int kb = r / 577, nb = r % 577, n0 = nb * 32; bf16_t* dst; int drow;
;             if (n0 < 6144) { dst = WIN1; drow = n0; }
;             else if (n0 < 8192) { dst = WIN2; drow = n0 - 6144; }
;             else if (n0 < 8224) { dst = WIN1; drow = 12288 + (n0 - 8192); }
;             else if (n0 < 10272) { dst = WIN1; drow = 6144 + (n0 - 8224); }
;             else if (n0 < 12320) { dst = WIN1; drow = 8192 + (n0 - 10272); }
;             else if (n0 < 14368) { dst = WIN1; drow = 10240 + (n0 - 12320); }
;             else if (n0 < 16416) { dst = WIN2; drow = 2048 + (n0 - 14368); }
;             else { dst = WIN2; drow = 4096 + (n0 - 16416); }
;             tr_item(p.w_in, 18464, kb * 64, n0, dst + (size_t)drow * 2048 + kb * 64, 2048, scr, lane); continue; }
.LBB0_19:
	s_lshl_b32 s80, s28, 3
	v_writelane_b32 v253, s60, 1
	s_nop 1
	v_writelane_b32 v253, s61, 2
	v_writelane_b32 v253, s34, 3
	s_nop 1
	v_writelane_b32 v253, s35, 4
	v_writelane_b32 v253, s2, 5
	s_or_b64 exec, exec, s[4:5]
	s_load_dwordx16 s[4:19], s[0:1], 0x40
	s_add_u32 s22, s26, 0x4200000
	s_addc_u32 s23, s27, 0
	s_add_u32 s54, s26, 0x7300000
	s_addc_u32 s55, s27, 0
	s_waitcnt lgkmcnt(0)
	v_writelane_b32 v253, s4, 6
	s_nop 1
	v_writelane_b32 v253, s5, 7
	v_writelane_b32 v253, s6, 8
	v_writelane_b32 v253, s7, 9
	v_writelane_b32 v253, s8, 10
	v_writelane_b32 v253, s9, 11
	v_writelane_b32 v253, s10, 12
	v_writelane_b32 v253, s11, 13
	v_writelane_b32 v253, s12, 14
	v_writelane_b32 v253, s13, 15
	v_writelane_b32 v253, s14, 16
	v_writelane_b32 v253, s15, 17
	v_writelane_b32 v253, s16, 18
	v_writelane_b32 v253, s17, 19
	v_writelane_b32 v253, s18, 20
	v_writelane_b32 v253, s19, 21
	s_load_dwordx16 s[4:19], s[0:1], 0x80
	s_add_u32 s0, s26, 0x8b00000
	s_addc_u32 s1, s27, 0
	s_waitcnt lgkmcnt(0)
	v_writelane_b32 v253, s4, 22
	s_nop 1
	v_writelane_b32 v253, s5, 23
	v_writelane_b32 v253, s6, 24
	v_writelane_b32 v253, s7, 25
	v_writelane_b32 v253, s8, 26
	v_writelane_b32 v253, s9, 27
	v_writelane_b32 v253, s10, 28
	v_writelane_b32 v253, s11, 29
	v_writelane_b32 v253, s12, 30
	v_writelane_b32 v253, s13, 31
	v_writelane_b32 v253, s14, 32
	v_writelane_b32 v253, s15, 33
	v_writelane_b32 v253, s16, 34
	v_writelane_b32 v253, s17, 35
	v_writelane_b32 v253, s18, 36
	v_writelane_b32 v253, s19, 37
	v_writelane_b32 v253, s0, 38
	s_nop 1
	v_writelane_b32 v253, s1, 39
	s_add_u32 s0, s26, 0x9b00000
	s_addc_u32 s1, s27, 0
	v_writelane_b32 v253, s0, 40
	s_nop 1
	v_writelane_b32 v253, s1, 41
	s_movk_i32 s0, 0x6020
	v_cmp_gt_i32_e32 vcc, s0, v26
	s_and_saveexec_b64 s[0:1], vcc
	s_cbranch_execz .LBB0_54
	v_and_b32_e32 v2, 0x7c, v86
	v_mul_u32_u24_e32 v3, 0x84, v27
	v_and_b32_e32 v12, 56, v21
	v_readlane_b32 s56, v253, 22
	v_add3_u32 v28, v19, v2, v3
	v_mul_u32_u24_e32 v4, 0x84, v12
	v_mov_b32_e32 v3, 0
	v_lshlrev_b32_e32 v5, 2, v20
	v_readlane_b32 s57, v253, 23
	v_readlane_b32 s58, v253, 24
	v_readlane_b32 s59, v253, 25
	v_readlane_b32 s60, v253, 26
	v_readlane_b32 s61, v253, 27
	v_readlane_b32 s62, v253, 28
	v_readlane_b32 s63, v253, 29
	v_readlane_b32 s64, v253, 30
	v_readlane_b32 s65, v253, 31
	v_readlane_b32 s66, v253, 32
	v_readlane_b32 s67, v253, 33
	v_readlane_b32 s68, v253, 34
	v_readlane_b32 s69, v253, 35
	v_readlane_b32 s70, v253, 36
	v_readlane_b32 s71, v253, 37
	v_add3_u32 v29, v19, v4, v5
	v_lshlrev_b32_e32 v14, 11, v20
	v_lshl_add_u64 v[4:5], s[62:63], 0, v[2:3]
	v_lshl_add_u64 v[6:7], s[60:61], 0, v[2:3]
	v_lshl_add_u64 v[8:9], s[58:59], 0, v[2:3]
	v_readlane_b32 s56, v253, 6
	v_or_b32_e32 v16, 0x4000, v14
	v_or_b32_e32 v20, 0x8000, v14
	v_or_b32_e32 v22, 0xc000, v14
	s_add_u32 s4, s26, 0x9300000
	v_readlane_b32 s57, v253, 7
	v_readlane_b32 s58, v253, 8
	v_readlane_b32 s59, v253, 9
	v_readlane_b32 s60, v253, 10
	v_readlane_b32 s61, v253, 11
	v_readlane_b32 s62, v253, 12
	v_readlane_b32 s63, v253, 13
	v_readlane_b32 s64, v253, 14
	v_readlane_b32 s65, v253, 15
	v_readlane_b32 s66, v253, 16
	v_readlane_b32 s67, v253, 17
	v_readlane_b32 s68, v253, 18
	v_readlane_b32 s69, v253, 19
	v_readlane_b32 s70, v253, 20
	v_readlane_b32 s71, v253, 21
	v_readlane_b32 s8, v253, 5
	s_movk_i32 s2, 0x4000
	s_mov_b32 s6, 0x8000
	s_mov_b32 s7, 0xc000
	s_addc_u32 s5, s27, 0
	v_lshl_add_u64 v[10:11], s[58:59], 0, v[2:3]
	v_lshl_add_u32 v30, s8, 8, v18
	s_lshl_b32 s40, s80, 5
	s_mov_b64 s[8:9], 0
	s_mov_b32 s41, 0x10000
	s_mov_b32 s46, 0x14000
	s_mov_b32 s47, 0x18000
	s_mov_b32 s48, 0x1c000
	s_mov_b32 s49, 0x20000
	s_mov_b32 s50, 0x24000
	s_mov_b32 s51, 0x28000
	s_mov_b32 s56, 0x2c000
	s_mov_b32 s57, 0x30000
	s_mov_b32 s58, 0x34000
	s_mov_b32 s59, 0x38000
	s_mov_b32 s60, 0x3c000
	s_mov_b32 s61, 0x40000
	s_mov_b32 s62, 0x44000
	s_mov_b32 s63, 0x48000
	s_mov_b32 s64, 0x4c000
	s_mov_b32 s65, 0x50000
	s_mov_b32 s66, 0x54000
	s_mov_b32 s67, 0x58000
	s_mov_b32 s68, 0x5c000
	s_mov_b32 s69, 0x60000
	s_mov_b32 s70, 0x64000
	s_mov_b32 s71, 0x68000
	s_mov_b32 s72, 0x6c000
	s_mov_b32 s73, 0x70000
	s_mov_b32 s74, 0x74000
	s_mov_b32 s75, 0x78000
	s_mov_b32 s76, 0x7c000
	s_mov_b32 s77, 0x12080
	v_add_u32_e32 v31, 0x400, v28
	v_add_u32_e32 v32, 0x800, v28
	v_add_u32_e32 v33, 0xc00, v28
	v_add_u32_e32 v34, 0x1000, v28
	v_add_u32_e32 v35, 0x1400, v28
	v_add_u32_e32 v36, 0x1800, v28
	v_add_u32_e32 v37, 0x1c00, v28
	v_lshlrev_b32_e32 v2, 1, v12
	v_lshlrev_b32_e32 v12, 1, v14
	v_lshlrev_b32_e32 v14, 1, v16
	v_lshlrev_b32_e32 v16, 1, v20
	v_lshlrev_b32_e32 v18, 1, v22
	s_branch .LBB0_24

; __device__ __forceinline__ void phase_postproc(const Params& p, LAS unsigned char* lds) {
;     ...
;     for (int item = blockIdx.x; item < 4 * 16 * 48; item += gridDim.x) {
;         const int s = item % 48, tile = (item / 48) & 15, b = item / 768;
;         const int c0 = s * 128 + cg8 * 16; const size_t row0 = (size_t)b * T_ + tile * 256 + ti * 4;
;         u32x4 xr[7][2];
; #pragma unroll
;         for (int j = 0; j < 7; ++j) {
;             const bf16_t* src = (ti > 0 || j >= 3) ? QKV + (row0 - 3 + j) * 6144 + c0 : HALO + ((size_t)((b * 16 + tile) * 3) + j) * 6144 + c0;
;             xr[j][0] = *(const u32x4*)src; xr[j][1] = *(const u32x4*)(src + 8);
;         }
;         f32x4 w[4][4];
; #pragma unroll
;         for (int j = 0; j < 4; ++j)
; #pragma unroll
;             for (int q = 0; q < 4; ++q) w[j][q] = *(const f32x4*)(p.conv_w + j * 6144 + c0 + 4 * q);
.LBB0_525:
	s_or_b64 exec, exec, s[12:13]
	v_lshl_add_u64 v[10:11], s[26:27], 0, v[14:15]
	v_lshl_add_u64 v[10:11], v[0:1], 1, v[10:11]
	v_lshl_add_u64 v[110:111], v[8:9], 0, v[4:5]
	v_readlane_b32 s44, v253, 6
	v_lshl_add_u64 v[6:7], v[10:11], 0, v[6:7]
	v_readlane_b32 s48, v253, 10
	v_readlane_b32 s49, v253, 11
	v_add_co_u32_e32 v112, vcc, s3, v110
	v_lshl_add_u64 v[10:11], v[6:7], 0, v[12:13]
	v_lshl_add_u64 v[12:13], v[0:1], 2, s[48:49]
	v_addc_co_u32_e32 v113, vcc, 0, v111, vcc
	v_lshl_add_u64 v[6:7], v[6:7], 0, v[16:17]
	s_mov_b64 s[12:13], 0x3000
	v_add_co_u32_e32 v0, vcc, s6, v12
	global_load_dwordx4 v[120:123], v[10:11], off
	global_load_dwordx4 v[124:127], v[10:11], off offset:16
	global_load_dwordx4 v[128:131], v[6:7], off
	global_load_dwordx4 v[84:87], v[2:3], off offset:16
	global_load_dwordx4 v[92:95], v[2:3], off
	v_lshl_add_u64 v[116:117], v[110:111], 0, s[12:13]
	v_addc_co_u32_e32 v1, vcc, 0, v13, vcc
	s_mov_b32 s12, 0xc000
	global_load_dwordx4 v[100:103], v[6:7], off offset:16
	global_load_dwordx4 v[96:99], v[110:111], off offset:16
	global_load_dwordx4 v[160:163], v[110:111], off
	s_nop 0
	global_load_dwordx4 v[4:7], v[12:13], off offset:16
	global_load_dwordx4 v[28:31], v[12:13], off
	v_add_co_u32_e32 v2, vcc, s12, v12
	s_mov_b32 s12, 0x12000
	s_nop 0
	v_addc_co_u32_e32 v3, vcc, 0, v13, vcc
	v_add_co_u32_e32 v8, vcc, s12, v12
	s_mov_b64 s[12:13], 0x9000
	s_nop 0
	v_addc_co_u32_e32 v9, vcc, 0, v13, vcc
	global_load_dwordx4 v[48:51], v[0:1], off
	global_load_dwordx4 v[52:55], v[2:3], off
	global_load_dwordx4 v[44:47], v[8:9], off
	v_add_co_u32_e32 v24, vcc, s6, v110
	v_lshl_add_u64 v[118:119], v[110:111], 0, s[12:13]
	s_nop 0
	v_addc_co_u32_e32 v25, vcc, 0, v111, vcc
	s_mov_b32 s12, 0x9000
	v_add_co_u32_e32 v14, vcc, s12, v110
	s_mov_b64 s[12:13], 0xc000
	v_lshl_add_u64 v[18:19], v[12:13], 0, s[12:13]
	s_mov_b64 s[12:13], 0x12000
	v_addc_co_u32_e32 v15, vcc, 0, v111, vcc
	v_lshl_add_u64 v[16:17], v[12:13], 0, s[8:9]
	v_lshl_add_u64 v[26:27], v[12:13], 0, s[12:13]
	v_lshl_add_u64 v[114:115], v[110:111], 0, s[8:9]
	global_load_dwordx4 v[0:3], v[12:13], off offset:48
	global_load_dwordx4 v[8:11], v[12:13], off offset:32
	global_load_dwordx4 v[88:91], v[112:113], off
	global_load_dwordx4 v[80:83], v[116:117], off offset:16
	global_load_dwordx4 v[72:75], v[114:115], off offset:16
	global_load_dwordx4 v[56:59], v[14:15], off
	s_nop 0
	global_load_dwordx4 v[12:15], v[16:17], off offset:48
	global_load_dwordx4 v[32:35], v[16:17], off offset:32
	global_load_dwordx4 v[60:63], v[16:17], off offset:16
	global_load_dwordx4 v[20:23], v[18:19], off offset:48
	global_load_dwordx4 v[40:43], v[18:19], off offset:32
	global_load_dwordx4 v[68:71], v[18:19], off offset:16
	s_nop 0
	global_load_dwordx4 v[16:19], v[26:27], off offset:48
	global_load_dwordx4 v[36:39], v[26:27], off offset:32
	global_load_dwordx4 v[64:67], v[26:27], off offset:16
	global_load_dwordx4 v[76:79], v[24:25], off
	s_nop 0
	global_load_dwordx4 v[24:27], v[118:119], off offset:16
	s_add_i32 s14, s10, s28
	s_cmpk_gt_i32 s14, 0xbff
	s_cselect_b32 s14, s10, s14
	s_lshr_b32 s15, s14, 4
	s_mul_hi_u32 s15, s15, 0xaaaaaaab
	s_lshr_b32 s15, s15, 1
	s_mul_i32 s16, s15, 48
	s_sub_i32 s16, s14, s16
	s_lshl_b32 s15, s15, 8
	s_mul_i32 s15, s15, 0x3000
	s_lshl_b32 s16, s16, 8
	s_add_i32 s15, s15, s16
	s_add_i32 s15, s15, 0xe408000
	v_lshrrev_b32_e32 v248, 1, v247
	v_and_b32_e32 v250, 1, v247
	v_mul_u32_u24_e32 v248, 0x3000, v248
	v_lshl_add_u32 v248, v250, 7, v248
	v_add_u32_e32 v248, s15, v248
	global_load_dword v249, v248, s[26:27]
	s_mulk_i32 s11, 0xffd0
	s_add_i32 s11, s10, s11
	s_cmp_lt_i32 s11, 32
	s_cselect_b64 s[12:13], -1, 0
	s_cmp_lt_i32 s11, 16
	s_cselect_b64 s[36:37], -1, 0
	s_cmp_gt_i32 s11, 31
	v_readlane_b32 s45, v253, 7
	v_readlane_b32 s46, v253, 8
	v_readlane_b32 s47, v253, 9
	v_readlane_b32 s50, v253, 12
	v_readlane_b32 s51, v253, 13
	v_readlane_b32 s52, v253, 14
	v_readlane_b32 s53, v253, 15
	v_readlane_b32 s54, v253, 16
	v_readlane_b32 s55, v253, 17
	v_readlane_b32 s56, v253, 18
	v_readlane_b32 s57, v253, 19
	v_readlane_b32 s58, v253, 20
	v_readlane_b32 s59, v253, 21
	s_waitcnt vmcnt(28)
	v_lshlrev_b32_e32 v154, 16, v128
	v_lshlrev_b32_e32 v182, 16, v122
	v_and_b32_e32 v183, 0xffff0000, v122
	v_lshlrev_b32_e32 v178, 16, v123
	v_and_b32_e32 v179, 0xffff0000, v123
	v_lshlrev_b32_e32 v156, 16, v124
	v_and_b32_e32 v157, 0xffff0000, v124
	v_lshlrev_b32_e32 v168, 16, v125
	v_and_b32_e32 v169, 0xffff0000, v125
	s_waitcnt vmcnt(24)
	v_lshlrev_b32_e32 v124, 16, v96
	v_and_b32_e32 v125, 0xffff0000, v96
	v_lshlrev_b32_e32 v122, 16, v97
	v_and_b32_e32 v123, 0xffff0000, v97
	v_lshlrev_b32_e32 v96, 16, v92
	v_and_b32_e32 v97, 0xffff0000, v92
	v_lshlrev_b32_e32 v158, 16, v120
	v_and_b32_e32 v159, 0xffff0000, v120
	v_lshlrev_b32_e32 v188, 16, v121
	v_and_b32_e32 v189, 0xffff0000, v121
	s_waitcnt vmcnt(21)
	v_pk_fma_f32 v[96:97], v[28:29], v[96:97], 0 op_sel_hi:[1,1,0]
	v_lshlrev_b32_e32 v120, 16, v93
	v_and_b32_e32 v121, 0xffff0000, v93
	v_and_b32_e32 v155, 0xffff0000, v128
	s_waitcnt vmcnt(20)
	v_pk_fma_f32 v[96:97], v[48:49], v[158:159], v[96:97]
	v_pk_fma_f32 v[120:121], v[30:31], v[120:121], 0 op_sel_hi:[1,1,0]
	v_lshlrev_b32_e32 v152, 16, v129
	v_and_b32_e32 v153, 0xffff0000, v129
	v_lshlrev_b32_e32 v136, 16, v160
	v_and_b32_e32 v137, 0xffff0000, v160
	s_waitcnt vmcnt(19)
	v_pk_fma_f32 v[96:97], v[52:53], v[154:155], v[96:97]
	v_pk_fma_f32 v[120:121], v[50:51], v[188:189], v[120:121]
	v_lshlrev_b32_e32 v132, 16, v161
	v_and_b32_e32 v133, 0xffff0000, v161
	s_waitcnt vmcnt(18)
; __device__ __forceinline__ float siluf_(float x) { return x * sigmoidf_(x); }
; __device__ __forceinline__ void phase_postproc(const Params& p, LAS unsigned char* lds) {
;     ...
;         u32x4 o[4][2];
; #pragma unroll
;         for (int r = 0; r < 4; ++r) {
;             float y[16];
; #pragma unroll
;             for (int i = 0; i < 16; ++i) y[i] = 0.f;
; #pragma unroll
;             for (int j = 0; j < 4; ++j) { float xf[16]; unpack8(xr[r + j][0], xf); unpack8(xr[r + j][1], xf + 8);
; #pragma unroll
;                 for (int q = 0; q < 4; ++q)
; #pragma unroll
;                     for (int e = 0; e < 4; ++e) y[4 * q + e] += w[j][q][e] * xf[4 * q + e]; }
;             float ss = 0.f;
; #pragma unroll
;             for (int i = 0; i < 16; ++i) { y[i] = siluf_(y[i]); ss += y[i] * y[i]; }
;             ss += __shfl_xor(ss, 1); ss += __shfl_xor(ss, 2); ss += __shfl_xor(ss, 4);
;             float sc = 1.0f;
;             if (s < 32) { sc = rsqrtf(ss + 1e-6f); if (s < 16) sc *= QSCALE; }
	v_pk_fma_f32 v[96:97], v[44:45], v[136:137], v[96:97]
	v_pk_fma_f32 v[120:121], v[54:55], v[152:153], v[120:121]
	v_lshlrev_b32_e32 v142, 16, v102
	v_and_b32_e32 v143, 0xffff0000, v102
	v_lshlrev_b32_e32 v140, 16, v103
	v_and_b32_e32 v141, 0xffff0000, v103
	v_lshlrev_b32_e32 v102, 16, v98
	v_and_b32_e32 v103, 0xffff0000, v98
	v_mul_f32_e32 v98, 0xbfb8aa3b, v97
	v_pk_fma_f32 v[120:121], v[46:47], v[132:133], v[120:121]
	v_exp_f32_e32 v98, v98
	v_mul_f32_e32 v93, 0xbfb8aa3b, v120
	v_lshlrev_b32_e32 v144, 16, v101
	v_and_b32_e32 v145, 0xffff0000, v101
	v_exp_f32_e32 v101, v93
	v_mul_f32_e32 v93, 0xbfb8aa3b, v121
	v_exp_f32_e32 v129, v93
	v_mul_f32_e32 v92, 0xbfb8aa3b, v96
	v_exp_f32_e32 v92, v92
	v_add_f32_e32 v98, 1.0, v98
	v_rcp_f32_e32 v93, v98
	v_add_f32_e32 v98, 1.0, v101
	v_rcp_f32_e32 v128, v98
	v_add_f32_e32 v98, 1.0, v129
	v_lshlrev_b32_e32 v146, 16, v100
	v_and_b32_e32 v147, 0xffff0000, v100
	v_lshlrev_b32_e32 v100, 16, v99
	v_rcp_f32_e32 v129, v98
	v_and_b32_e32 v101, 0xffff0000, v99
	v_lshlrev_b32_e32 v98, 16, v94
	v_and_b32_e32 v99, 0xffff0000, v94
	v_add_f32_e32 v92, 1.0, v92
	v_pk_fma_f32 v[98:99], v[4:5], v[98:99], 0 op_sel_hi:[1,1,0]
	v_lshlrev_b32_e32 v150, 16, v130
	v_and_b32_e32 v151, 0xffff0000, v130
	v_rcp_f32_e32 v92, v92
	s_waitcnt vmcnt(9)
	v_pk_fma_f32 v[98:99], v[60:61], v[182:183], v[98:99]
	v_lshlrev_b32_e32 v148, 16, v131
	v_and_b32_e32 v149, 0xffff0000, v131
	v_lshlrev_b32_e32 v130, 16, v162
	v_and_b32_e32 v131, 0xffff0000, v162
	s_waitcnt vmcnt(6)
	v_pk_fma_f32 v[98:99], v[68:69], v[150:151], v[98:99]
	v_pk_mul_f32 v[92:93], v[96:97], v[92:93]
	s_waitcnt vmcnt(3)
	v_pk_fma_f32 v[98:99], v[64:65], v[130:131], v[98:99]
	v_pk_mul_f32 v[96:97], v[120:121], v[128:129]
	v_mul_f32_e32 v94, 0xbfb8aa3b, v98
	v_exp_f32_e32 v94, v94
	v_mul_f32_e32 v120, 0xbfb8aa3b, v99
	v_exp_f32_e32 v121, v120
	v_lshlrev_b32_e32 v164, 16, v126
	v_add_f32_e32 v94, 1.0, v94
	v_rcp_f32_e32 v120, v94
	v_add_f32_e32 v94, 1.0, v121
	v_rcp_f32_e32 v121, v94
	v_lshlrev_b32_e32 v94, 16, v95
	v_and_b32_e32 v95, 0xffff0000, v95
	v_pk_fma_f32 v[94:95], v[6:7], v[94:95], 0 op_sel_hi:[1,1,0]
	v_and_b32_e32 v165, 0xffff0000, v126
	v_pk_fma_f32 v[94:95], v[62:63], v[178:179], v[94:95]
	v_lshlrev_b32_e32 v166, 16, v127
	v_and_b32_e32 v167, 0xffff0000, v127
	v_lshlrev_b32_e32 v126, 16, v163
	v_and_b32_e32 v127, 0xffff0000, v163
	v_pk_fma_f32 v[94:95], v[70:71], v[148:149], v[94:95]
	v_lshlrev_b32_e32 v176, 16, v86
	v_pk_fma_f32 v[128:129], v[66:67], v[126:127], v[94:95]
	v_and_b32_e32 v177, 0xffff0000, v86
	v_mul_f32_e32 v94, 0xbfb8aa3b, v128
	v_exp_f32_e32 v134, v94
	v_mul_f32_e32 v94, 0xbfb8aa3b, v129
	v_exp_f32_e32 v138, v94
	v_pk_mul_f32 v[94:95], v[98:99], v[120:121]
	v_lshlrev_b32_e32 v120, 16, v84
	v_and_b32_e32 v121, 0xffff0000, v84
	v_pk_fma_f32 v[120:121], v[8:9], v[120:121], 0 op_sel_hi:[1,1,0]
	v_add_f32_e32 v98, 1.0, v134
	v_pk_fma_f32 v[120:121], v[32:33], v[156:157], v[120:121]
	v_add_f32_e32 v99, 1.0, v138
	v_pk_fma_f32 v[120:121], v[40:41], v[146:147], v[120:121]
	v_rcp_f32_e32 v98, v98
	v_pk_fma_f32 v[120:121], v[36:37], v[124:125], v[120:121]
	v_rcp_f32_e32 v99, v99
	v_mul_f32_e32 v84, 0xbfb8aa3b, v120
	v_exp_f32_e32 v84, v84
	v_mul_f32_e32 v134, 0xbfb8aa3b, v121
	v_exp_f32_e32 v134, v134
	v_pk_mul_f32 v[98:99], v[128:129], v[98:99]
	v_add_f32_e32 v84, 1.0, v84
	v_rcp_f32_e32 v170, v84
	v_add_f32_e32 v84, 1.0, v134
	v_rcp_f32_e32 v171, v84
	v_lshlrev_b32_e32 v84, 16, v85
	v_and_b32_e32 v85, 0xffff0000, v85
	v_pk_fma_f32 v[84:85], v[10:11], v[84:85], 0 op_sel_hi:[1,1,0]
	v_pk_fma_f32 v[176:177], v[0:1], v[176:177], 0 op_sel_hi:[1,1,0]
	v_pk_fma_f32 v[84:85], v[34:35], v[168:169], v[84:85]
	v_pk_fma_f32 v[176:177], v[12:13], v[164:165], v[176:177]
	v_pk_fma_f32 v[84:85], v[42:43], v[144:145], v[84:85]
	v_pk_fma_f32 v[176:177], v[20:21], v[142:143], v[176:177]
	v_pk_fma_f32 v[84:85], v[38:39], v[122:123], v[84:85]
	v_pk_fma_f32 v[176:177], v[16:17], v[102:103], v[176:177]
	v_mul_f32_e32 v128, 0xbfb8aa3b, v84
	v_mul_f32_e32 v129, 0xbfb8aa3b, v85
	v_exp_f32_e32 v128, v128
	v_exp_f32_e32 v129, v129
	v_mul_f32_e32 v134, 0xbfb8aa3b, v177
	v_exp_f32_e32 v134, v134
	v_add_f32_e32 v128, 1.0, v128
	v_add_f32_e32 v129, 1.0, v129
	v_rcp_f32_e32 v128, v128
	v_rcp_f32_e32 v129, v129
	v_pk_mul_f32 v[160:161], v[92:93], v[92:93]
	v_mul_f32_e32 v86, 0xbfb8aa3b, v176
	v_add_f32_e32 v134, 1.0, v134
	v_pk_mul_f32 v[84:85], v[84:85], v[128:129]
	v_lshlrev_b32_e32 v128, 16, v87
	v_and_b32_e32 v129, 0xffff0000, v87
	v_pk_fma_f32 v[128:129], v[2:3], v[128:129], 0 op_sel_hi:[1,1,0]
	v_pk_mul_f32 v[162:163], v[96:97], v[96:97]
	v_pk_fma_f32 v[128:129], v[14:15], v[166:167], v[128:129]
	v_exp_f32_e32 v86, v86
	v_pk_fma_f32 v[128:129], v[22:23], v[140:141], v[128:129]
	v_pk_mul_f32 v[172:173], v[94:95], v[94:95]
	v_pk_fma_f32 v[180:181], v[18:19], v[100:101], v[128:129]
	v_pk_mul_f32 v[174:175], v[98:99], v[98:99]
	v_mul_f32_e32 v87, 0xbfb8aa3b, v180
	v_exp_f32_e32 v128, v87
	v_mul_f32_e32 v87, 0xbfb8aa3b, v181
	v_exp_f32_e32 v129, v87
	v_rcp_f32_e32 v87, v134
	v_add_f32_e32 v134, v160, v161
	v_add_f32_e32 v134, v162, v134
	v_add_f32_e32 v134, v163, v134
	v_add_f32_e32 v134, v172, v134
	v_add_f32_e32 v86, 1.0, v86
	v_add_f32_e32 v134, v173, v134
	v_pk_mul_f32 v[120:121], v[120:121], v[170:171]
	v_rcp_f32_e32 v86, v86
	v_add_f32_e32 v128, 1.0, v128
	v_add_f32_e32 v134, v174, v134
	v_pk_mul_f32 v[170:171], v[120:121], v[120:121]
	v_rcp_f32_e32 v190, v128
	v_add_f32_e32 v128, 1.0, v129
	v_add_f32_e32 v134, v175, v134
	v_rcp_f32_e32 v191, v128
	v_add_f32_e32 v134, v170, v134
	v_pk_mul_f32 v[192:193], v[84:85], v[84:85]
	v_add_f32_e32 v134, v171, v134
	v_pk_mul_f32 v[128:129], v[176:177], v[86:87]
	v_add_f32_e32 v134, v192, v134
	v_pk_mul_f32 v[176:177], v[128:129], v[128:129]
	v_add_f32_e32 v134, v193, v134
	v_pk_mul_f32 v[86:87], v[180:181], v[190:191]
	v_add_f32_e32 v134, v176, v134
	v_pk_mul_f32 v[180:181], v[86:87], v[86:87]
	v_add_f32_e32 v134, v177, v134
	v_add_f32_e32 v134, v180, v134
	v_add_f32_e32 v134, v181, v134
	ds_bpermute_b32 v138, v105, v134
	s_waitcnt lgkmcnt(0)
	v_add_f32_e32 v134, v134, v138
	ds_bpermute_b32 v138, v109, v134
	s_waitcnt lgkmcnt(0)
	v_add_f32_e32 v160, v134, v138
	ds_bpermute_b32 v161, v135, v160
	v_mov_b32_e32 v138, 1.0
	v_mov_b32_e32 v134, 1.0
	s_cbranch_scc1 .LBB0_527
	s_waitcnt lgkmcnt(0)
	v_add_f32_e32 v134, v160, v161
	v_add_f32_e32 v134, 0x358637bd, v134
	v_mul_f32_e32 v160, 0x4b800000, v134
	v_cmp_gt_f32_e32 vcc, s7, v134
	s_nop 1
	v_cndmask_b32_e32 v134, v134, v160, vcc
	v_rsq_f32_e32 v134, v134
	s_nop 0
	v_mul_f32_e32 v160, 0x45800000, v134
	v_cndmask_b32_e32 v134, v134, v160, vcc
	v_mul_f32_e32 v160, 0x3db504f3, v134
	v_cndmask_b32_e64 v134, v134, v160, s[36:37]

; __device__ __forceinline__ float siluf_(float x) { return x * sigmoidf_(x); }
; __device__ __forceinline__ void phase_postproc(const Params& p, LAS unsigned char* lds) {
;     ...
;         for (int r = 0; r < 4; ++r) {
;             float y[16];
; #pragma unroll
;             for (int i = 0; i < 16; ++i) y[i] = 0.f;
; #pragma unroll
;             for (int j = 0; j < 4; ++j) { float xf[16]; unpack8(xr[r + j][0], xf); unpack8(xr[r + j][1], xf + 8);
; #pragma unroll
;                 for (int q = 0; q < 4; ++q)
; #pragma unroll
;                     for (int e = 0; e < 4; ++e) y[4 * q + e] += w[j][q][e] * xf[4 * q + e]; }
;             float ss = 0.f;
; #pragma unroll
;             for (int i = 0; i < 16; ++i) { y[i] = siluf_(y[i]); ss += y[i] * y[i]; }
;             ss += __shfl_xor(ss, 1); ss += __shfl_xor(ss, 2); ss += __shfl_xor(ss, 4);
;             float sc = 1.0f;
;             if (s < 32) { sc = rsqrtf(ss + 1e-6f); if (s < 16) sc *= QSCALE; }
.LBB0_529:
	v_lshlrev_b32_e32 v188, 16, v72
	v_and_b32_e32 v189, 0xffff0000, v72
	v_lshlrev_b32_e32 v182, 16, v73
	v_and_b32_e32 v183, 0xffff0000, v73
	v_pk_fma_f32 v[72:73], v[28:29], v[154:155], 0 op_sel_hi:[1,1,0]
	s_waitcnt vmcnt(2)
	v_lshlrev_b32_e32 v196, 16, v76
	v_pk_fma_f32 v[72:73], v[48:49], v[136:137], v[72:73]
	v_and_b32_e32 v197, 0xffff0000, v76
	v_pk_fma_f32 v[72:73], v[52:53], v[180:181], v[72:73]
	v_lshlrev_b32_e32 v178, 16, v74
	v_pk_fma_f32 v[72:73], v[44:45], v[196:197], v[72:73]
	s_waitcnt lgkmcnt(0)
	v_and_b32_e32 v179, 0xffff0000, v74
	v_mul_f32_e32 v74, 0xbfb8aa3b, v72
	v_exp_f32_e32 v74, v74
	v_mul_f32_e32 v76, 0xbfb8aa3b, v73
	v_lshlrev_b32_e32 v194, 16, v77
	v_and_b32_e32 v195, 0xffff0000, v77
	v_exp_f32_e32 v77, v76
	v_pk_fma_f32 v[152:153], v[30:31], v[152:153], 0 op_sel_hi:[1,1,0]
	v_add_f32_e32 v74, 1.0, v74
	v_pk_fma_f32 v[152:153], v[50:51], v[132:133], v[152:153]
	v_rcp_f32_e32 v76, v74
	v_pk_fma_f32 v[152:153], v[54:55], v[176:177], v[152:153]
	v_add_f32_e32 v74, 1.0, v77
	v_pk_fma_f32 v[152:153], v[46:47], v[194:195], v[152:153]
	v_lshlrev_b32_e32 v190, 16, v79
	v_mul_f32_e32 v77, 0xbfb8aa3b, v152
	v_and_b32_e32 v191, 0xffff0000, v79
	v_exp_f32_e32 v79, v77
	v_mul_f32_e32 v77, 0xbfb8aa3b, v153
	v_exp_f32_e32 v155, v77
	v_rcp_f32_e32 v77, v74
	v_lshlrev_b32_e32 v192, 16, v78
	v_and_b32_e32 v193, 0xffff0000, v78
	v_add_f32_e32 v74, 1.0, v79
	v_pk_mul_f32 v[72:73], v[72:73], v[76:77]
	v_pk_fma_f32 v[76:77], v[4:5], v[150:151], 0 op_sel_hi:[1,1,0]
	v_rcp_f32_e32 v154, v74
	v_pk_fma_f32 v[76:77], v[60:61], v[130:131], v[76:77]
	v_add_f32_e32 v74, 1.0, v155
	v_pk_fma_f32 v[76:77], v[68:69], v[174:175], v[76:77]
	v_rcp_f32_e32 v155, v74
	v_pk_fma_f32 v[76:77], v[64:65], v[192:193], v[76:77]
	v_pk_fma_f32 v[148:149], v[6:7], v[148:149], 0 op_sel_hi:[1,1,0]
	v_mul_f32_e32 v150, 0xbfb8aa3b, v76
	v_mul_f32_e32 v151, 0xbfb8aa3b, v77
	v_exp_f32_e32 v150, v150
	v_exp_f32_e32 v151, v151
	v_pk_fma_f32 v[148:149], v[62:63], v[126:127], v[148:149]
	v_lshlrev_b32_e32 v78, 16, v75
	v_pk_fma_f32 v[148:149], v[70:71], v[172:173], v[148:149]
	v_and_b32_e32 v79, 0xffff0000, v75
	v_pk_fma_f32 v[148:149], v[66:67], v[190:191], v[148:149]
	v_pk_mul_f32 v[74:75], v[152:153], v[154:155]
	v_add_f32_e32 v150, 1.0, v150
	v_add_f32_e32 v151, 1.0, v151
	v_mul_f32_e32 v154, 0xbfb8aa3b, v148
	v_mul_f32_e32 v155, 0xbfb8aa3b, v149
	v_rcp_f32_e32 v150, v150
	v_rcp_f32_e32 v151, v151
	v_exp_f32_e32 v154, v154
	v_exp_f32_e32 v155, v155
	v_pk_fma_f32 v[146:147], v[8:9], v[146:147], 0 op_sel_hi:[1,1,0]
	v_pk_mul_f32 v[76:77], v[76:77], v[150:151]
	v_pk_fma_f32 v[146:147], v[32:33], v[124:125], v[146:147]
	v_add_f32_e32 v150, 1.0, v154
	v_pk_fma_f32 v[146:147], v[40:41], v[170:171], v[146:147]
	v_add_f32_e32 v151, 1.0, v155
	v_pk_fma_f32 v[154:155], v[36:37], v[188:189], v[146:147]
	v_rcp_f32_e32 v150, v150
	v_mul_f32_e32 v146, 0xbfb8aa3b, v154
	v_exp_f32_e32 v146, v146
	v_mul_f32_e32 v147, 0xbfb8aa3b, v155
	v_exp_f32_e32 v147, v147
	v_rcp_f32_e32 v151, v151
	v_pk_fma_f32 v[144:145], v[10:11], v[144:145], 0 op_sel_hi:[1,1,0]
	v_add_f32_e32 v146, 1.0, v146
	v_pk_fma_f32 v[144:145], v[34:35], v[122:123], v[144:145]
	v_rcp_f32_e32 v202, v146
	v_pk_fma_f32 v[144:145], v[42:43], v[162:163], v[144:145]
	v_add_f32_e32 v146, 1.0, v147
	v_pk_fma_f32 v[144:145], v[38:39], v[182:183], v[144:145]
	v_rcp_f32_e32 v203, v146
	v_pk_mul_f32 v[146:147], v[148:149], v[150:151]
	v_mul_f32_e32 v150, 0xbfb8aa3b, v144
	v_mul_f32_e32 v151, 0xbfb8aa3b, v145
	v_exp_f32_e32 v150, v150
	v_exp_f32_e32 v151, v151
	v_pk_fma_f32 v[142:143], v[0:1], v[142:143], 0 op_sel_hi:[1,1,0]
	v_pk_mul_f32 v[148:149], v[154:155], v[202:203]
	v_pk_fma_f32 v[142:143], v[12:13], v[102:103], v[142:143]
	v_add_f32_e32 v150, 1.0, v150
	v_pk_fma_f32 v[142:143], v[20:21], v[160:161], v[142:143]
	v_add_f32_e32 v151, 1.0, v151
	v_pk_fma_f32 v[202:203], v[16:17], v[178:179], v[142:143]
	v_rcp_f32_e32 v150, v150
	v_mul_f32_e32 v142, 0xbfb8aa3b, v202
	v_rcp_f32_e32 v151, v151
	v_exp_f32_e32 v199, v142
	v_pk_fma_f32 v[140:141], v[2:3], v[140:141], 0 op_sel_hi:[1,1,0]
	v_pk_mul_f32 v[200:201], v[72:73], v[72:73]
	v_pk_fma_f32 v[140:141], v[14:15], v[100:101], v[140:141]
	v_mul_f32_e32 v142, 0xbfb8aa3b, v203
	v_pk_fma_f32 v[140:141], v[22:23], v[158:159], v[140:141]
	v_pk_mul_f32 v[152:153], v[74:75], v[74:75]
	v_pk_fma_f32 v[140:141], v[18:19], v[78:79], v[140:141]
	v_exp_f32_e32 v208, v142
	v_pk_mul_f32 v[142:143], v[144:145], v[150:151]
	v_add_f32_e32 v144, 1.0, v199
	v_mul_f32_e32 v150, 0xbfb8aa3b, v140
	v_add_f32_e32 v199, v200, v201
	v_exp_f32_e32 v150, v150
	v_mul_f32_e32 v151, 0xbfb8aa3b, v141
	v_add_f32_e32 v152, v152, v199
	v_pk_mul_f32 v[204:205], v[76:77], v[76:77]
	v_exp_f32_e32 v151, v151
	v_add_f32_e32 v152, v153, v152
	v_add_f32_e32 v152, v204, v152
	v_pk_mul_f32 v[206:207], v[146:147], v[146:147]
	v_add_f32_e32 v145, 1.0, v208
	v_add_f32_e32 v152, v205, v152
	v_rcp_f32_e32 v144, v144
	v_rcp_f32_e32 v145, v145
	v_add_f32_e32 v150, 1.0, v150
	v_add_f32_e32 v152, v206, v152
	v_pk_mul_f32 v[154:155], v[148:149], v[148:149]
	v_rcp_f32_e32 v208, v150
	v_add_f32_e32 v150, 1.0, v151
	v_add_f32_e32 v152, v207, v152
	v_rcp_f32_e32 v209, v150
	v_add_f32_e32 v152, v154, v152
	v_pk_mul_f32 v[210:211], v[142:143], v[142:143]
	v_add_f32_e32 v152, v155, v152
	v_pk_mul_f32 v[150:151], v[202:203], v[144:145]
	v_add_f32_e32 v152, v210, v152
	v_pk_mul_f32 v[202:203], v[150:151], v[150:151]
	v_add_f32_e32 v152, v211, v152
	v_pk_mul_f32 v[144:145], v[140:141], v[208:209]
	v_add_f32_e32 v152, v202, v152
	v_pk_mul_f32 v[140:141], v[144:145], v[144:145]
	v_add_f32_e32 v152, v203, v152
	v_add_f32_e32 v140, v140, v152
	v_add_f32_e32 v140, v141, v140
	ds_bpermute_b32 v141, v105, v140
	s_and_b64 vcc, exec, s[38:39]
	v_mov_b32_e32 v152, 1.0
	s_waitcnt lgkmcnt(0)
	v_add_f32_e32 v140, v140, v141
	ds_bpermute_b32 v141, v109, v140
	s_waitcnt lgkmcnt(0)
	v_add_f32_e32 v141, v140, v141
	ds_bpermute_b32 v153, v135, v141
	v_mov_b32_e32 v140, 1.0
	s_cbranch_vccnz .LBB0_531
	s_waitcnt lgkmcnt(0)
	v_add_f32_e32 v141, v141, v153
	v_add_f32_e32 v141, 0x358637bd, v141
	v_mul_f32_e32 v152, 0x4b800000, v141
	v_cmp_gt_f32_e32 vcc, s7, v141
	s_nop 1
	v_cndmask_b32_e32 v141, v141, v152, vcc
	v_rsq_f32_e32 v141, v141
	s_nop 0
	v_mul_f32_e32 v152, 0x45800000, v141
	v_cndmask_b32_e32 v141, v141, v152, vcc
	v_mul_f32_e32 v152, 0x3db504f3, v141
	v_cndmask_b32_e64 v152, v141, v152, s[36:37]
; __device__ __forceinline__ float siluf_(float x) { return x * sigmoidf_(x); }
; __device__ __forceinline__ void phase_postproc(const Params& p, LAS unsigned char* lds) {
;     ...
;         for (int r = 0; r < 4; ++r) {
;             float y[16];
; #pragma unroll
;             for (int i = 0; i < 16; ++i) y[i] = 0.f;
; #pragma unroll
;             for (int j = 0; j < 4; ++j) { float xf[16]; unpack8(xr[r + j][0], xf); unpack8(xr[r + j][1], xf + 8);
; #pragma unroll
;                 for (int q = 0; q < 4; ++q)
; #pragma unroll
;                     for (int e = 0; e < 4; ++e) y[4 * q + e] += w[j][q][e] * xf[4 * q + e]; }
;             float ss = 0.f;
; #pragma unroll
;             for (int i = 0; i < 16; ++i) { y[i] = siluf_(y[i]); ss += y[i] * y[i]; }
;             ss += __shfl_xor(ss, 1); ss += __shfl_xor(ss, 2); ss += __shfl_xor(ss, 4);
;             float sc = 1.0f;
;             if (s < 32) { sc = rsqrtf(ss + 1e-6f); if (s < 16) sc *= QSCALE; }
.LBB0_531:
	v_pk_fma_f32 v[28:29], v[28:29], v[136:137], 0 op_sel_hi:[1,1,0]
	v_pk_fma_f32 v[30:31], v[30:31], v[132:133], 0 op_sel_hi:[1,1,0]
	v_pk_fma_f32 v[28:29], v[48:49], v[180:181], v[28:29]
	v_lshlrev_b32_e32 v48, 16, v56
	v_pk_fma_f32 v[28:29], v[52:53], v[196:197], v[28:29]
	v_and_b32_e32 v49, 0xffff0000, v56
	v_pk_fma_f32 v[30:31], v[50:51], v[176:177], v[30:31]
	v_pk_fma_f32 v[28:29], v[44:45], v[48:49], v[28:29]
	v_pk_fma_f32 v[30:31], v[54:55], v[194:195], v[30:31]
	v_lshlrev_b32_e32 v48, 16, v57
	v_and_b32_e32 v49, 0xffff0000, v57
	v_pk_fma_f32 v[30:31], v[46:47], v[48:49], v[30:31]
	v_pk_fma_f32 v[8:9], v[8:9], v[124:125], 0 op_sel_hi:[1,1,0]
	v_mul_f32_e32 v46, 0xbfb8aa3b, v30
	v_mul_f32_e32 v47, 0xbfb8aa3b, v31
	v_exp_f32_e32 v46, v46
	v_exp_f32_e32 v47, v47
	v_pk_fma_f32 v[8:9], v[32:33], v[170:171], v[8:9]
	s_waitcnt vmcnt(1)
	v_lshlrev_b32_e32 v32, 16, v24
	v_add_f32_e32 v46, 1.0, v46
	v_add_f32_e32 v47, 1.0, v47
	v_rcp_f32_e32 v46, v46
	v_rcp_f32_e32 v47, v47
	v_pk_fma_f32 v[8:9], v[40:41], v[188:189], v[8:9]
	v_and_b32_e32 v33, 0xffff0000, v24
	v_pk_fma_f32 v[8:9], v[36:37], v[32:33], v[8:9]
	v_pk_fma_f32 v[4:5], v[4:5], v[130:131], 0 op_sel_hi:[1,1,0]
	v_mul_f32_e32 v24, 0xbfb8aa3b, v8
	v_pk_fma_f32 v[4:5], v[60:61], v[174:175], v[4:5]
	v_exp_f32_e32 v24, v24
	v_mul_f32_e32 v32, 0xbfb8aa3b, v9
	v_pk_mul_f32 v[30:31], v[30:31], v[46:47]
	v_pk_fma_f32 v[4:5], v[68:69], v[192:193], v[4:5]
	v_lshlrev_b32_e32 v46, 16, v58
	v_and_b32_e32 v47, 0xffff0000, v58
	v_exp_f32_e32 v33, v32
	v_pk_fma_f32 v[4:5], v[64:65], v[46:47], v[4:5]
	v_mul_f32_e32 v44, 0xbfb8aa3b, v28
	v_mul_f32_e32 v46, 0xbfb8aa3b, v4
	v_mul_f32_e32 v45, 0xbfb8aa3b, v29
	v_exp_f32_e32 v48, v46
	v_mul_f32_e32 v46, 0xbfb8aa3b, v5
	v_add_f32_e32 v24, 1.0, v24
	v_exp_f32_e32 v44, v44
	v_exp_f32_e32 v45, v45
	v_exp_f32_e32 v49, v46
	v_pk_fma_f32 v[6:7], v[6:7], v[126:127], 0 op_sel_hi:[1,1,0]
	v_rcp_f32_e32 v32, v24
	v_add_f32_e32 v24, 1.0, v33
	v_pk_fma_f32 v[10:11], v[10:11], v[122:123], 0 op_sel_hi:[1,1,0]
	v_pk_fma_f32 v[6:7], v[62:63], v[172:173], v[6:7]
	v_rcp_f32_e32 v33, v24
	v_pk_fma_f32 v[10:11], v[34:35], v[162:163], v[10:11]
	v_pk_fma_f32 v[6:7], v[70:71], v[190:191], v[6:7]
	v_lshlrev_b32_e32 v50, 16, v59
	v_and_b32_e32 v51, 0xffff0000, v59
	v_pk_fma_f32 v[10:11], v[42:43], v[182:183], v[10:11]
	v_lshlrev_b32_e32 v24, 16, v25
	v_and_b32_e32 v25, 0xffff0000, v25
	v_pk_fma_f32 v[6:7], v[66:67], v[50:51], v[6:7]
	v_pk_fma_f32 v[10:11], v[38:39], v[24:25], v[10:11]
	v_add_f32_e32 v44, 1.0, v44
	v_add_f32_e32 v45, 1.0, v45
	v_add_f32_e32 v48, 1.0, v48
	v_add_f32_e32 v49, 1.0, v49
	v_mul_f32_e32 v50, 0xbfb8aa3b, v6
	v_mul_f32_e32 v51, 0xbfb8aa3b, v7
	v_mul_f32_e32 v24, 0xbfb8aa3b, v10
	v_rcp_f32_e32 v44, v44
	v_rcp_f32_e32 v45, v45
	v_rcp_f32_e32 v48, v48
	v_rcp_f32_e32 v49, v49
	v_exp_f32_e32 v50, v50
	v_exp_f32_e32 v51, v51
	v_pk_mul_f32 v[8:9], v[8:9], v[32:33]
	v_exp_f32_e32 v32, v24
	v_mul_f32_e32 v24, 0xbfb8aa3b, v11
	v_pk_fma_f32 v[0:1], v[0:1], v[102:103], 0 op_sel_hi:[1,1,0]
	v_exp_f32_e32 v33, v24
	v_pk_fma_f32 v[0:1], v[12:13], v[160:161], v[0:1]
	v_lshlrev_b32_e32 v12, 16, v26
	v_pk_fma_f32 v[0:1], v[20:21], v[178:179], v[0:1]
	v_and_b32_e32 v13, 0xffff0000, v26
	v_pk_fma_f32 v[12:13], v[16:17], v[12:13], v[0:1]
	v_pk_fma_f32 v[2:3], v[2:3], v[100:101], 0 op_sel_hi:[1,1,0]
	v_pk_mul_f32 v[28:29], v[28:29], v[44:45]
	v_pk_mul_f32 v[4:5], v[4:5], v[48:49]
	v_add_f32_e32 v48, 1.0, v50
	v_add_f32_e32 v49, 1.0, v51
	v_mul_f32_e32 v0, 0xbfb8aa3b, v12
	v_pk_fma_f32 v[2:3], v[14:15], v[158:159], v[2:3]
	v_pk_mul_f32 v[44:45], v[28:29], v[28:29]
	v_rcp_f32_e32 v48, v48
	v_rcp_f32_e32 v49, v49
	v_add_f32_e32 v32, 1.0, v32
	v_add_f32_e32 v33, 1.0, v33
	v_exp_f32_e32 v16, v0
	v_mul_f32_e32 v0, 0xbfb8aa3b, v13
	v_pk_fma_f32 v[2:3], v[22:23], v[78:79], v[2:3]
	v_lshlrev_b32_e32 v14, 16, v27
	v_and_b32_e32 v15, 0xffff0000, v27
	v_pk_mul_f32 v[46:47], v[30:31], v[30:31]
	v_rcp_f32_e32 v32, v32
	v_rcp_f32_e32 v33, v33
	v_exp_f32_e32 v17, v0
	v_pk_fma_f32 v[2:3], v[18:19], v[14:15], v[2:3]
	v_add_f32_e32 v18, v44, v45
	v_mul_f32_e32 v14, 0xbfb8aa3b, v2
	v_mul_f32_e32 v15, 0xbfb8aa3b, v3
	v_add_f32_e32 v18, v46, v18
	v_pk_mul_f32 v[36:37], v[4:5], v[4:5]
	v_exp_f32_e32 v14, v14
	v_exp_f32_e32 v15, v15
	v_add_f32_e32 v18, v47, v18
	v_pk_mul_f32 v[6:7], v[6:7], v[48:49]
	v_add_f32_e32 v18, v36, v18
	v_pk_mul_f32 v[40:41], v[6:7], v[6:7]
	v_pk_mul_f32 v[0:1], v[10:11], v[32:33]
	v_add_f32_e32 v10, 1.0, v16
	v_add_f32_e32 v11, 1.0, v17
	v_add_f32_e32 v18, v37, v18
	v_rcp_f32_e32 v10, v10
	v_rcp_f32_e32 v11, v11
	v_add_f32_e32 v18, v40, v18
	v_pk_mul_f32 v[24:25], v[8:9], v[8:9]
	v_add_f32_e32 v14, 1.0, v14
	v_add_f32_e32 v15, 1.0, v15
	v_add_f32_e32 v18, v41, v18
	v_rcp_f32_e32 v14, v14
	v_rcp_f32_e32 v15, v15
	v_add_f32_e32 v18, v24, v18
	v_pk_mul_f32 v[16:17], v[0:1], v[0:1]
	v_add_f32_e32 v18, v25, v18
	v_pk_mul_f32 v[10:11], v[12:13], v[10:11]
	v_add_f32_e32 v16, v16, v18
	v_pk_mul_f32 v[12:13], v[10:11], v[10:11]
	v_add_f32_e32 v16, v17, v16
	v_pk_mul_f32 v[2:3], v[2:3], v[14:15]
	v_add_f32_e32 v12, v12, v16
	v_pk_mul_f32 v[14:15], v[2:3], v[2:3]
	v_add_f32_e32 v12, v13, v12
	v_add_f32_e32 v12, v14, v12
	v_add_f32_e32 v12, v15, v12
	ds_bpermute_b32 v13, v105, v12
	s_and_b64 vcc, exec, s[38:39]
	s_waitcnt lgkmcnt(0)
	v_add_f32_e32 v12, v12, v13
	ds_bpermute_b32 v13, v109, v12
	s_waitcnt lgkmcnt(0)
	v_add_f32_e32 v12, v12, v13
	ds_bpermute_b32 v13, v135, v12
	s_cbranch_vccnz .LBB0_520
	s_waitcnt lgkmcnt(0)
	v_add_f32_e32 v12, v12, v13
	v_add_f32_e32 v12, 0x358637bd, v12
	v_mul_f32_e32 v13, 0x4b800000, v12
	v_cmp_gt_f32_e32 vcc, s7, v12
	s_nop 1
	v_cndmask_b32_e32 v12, v12, v13, vcc
	v_rsq_f32_e32 v12, v12
	s_nop 0
	v_mul_f32_e32 v13, 0x45800000, v12
	v_cndmask_b32_e32 v12, v12, v13, vcc
	v_mul_f32_e32 v13, 0x3db504f3, v12
	v_cndmask_b32_e64 v140, v12, v13, s[36:37]
	s_branch .LBB0_520
